# v51 + attention far fast path: branch into the far-block body right after the near/far compare (skips bias-register init and exec save/restore)
# baseline (speedup 1.0000x reference)
.Lfar_a2:
	s_lshl_b32 s13, s29, 6
	s_mul_i32 s12, s29, 0x2200
	s_add_i32 s13, s13, 0
	v_add_u32_e32 v171, s12, v139
	ds_read_b128 v[222:225], v171 offset:1024
	ds_read_b128 v[226:229], v171 offset:1088
	ds_read_b128 v[230:233], v171 offset:2112
	ds_read_b128 v[234:237], v171 offset:2176
	s_waitcnt lgkmcnt(4)
	s_waitcnt lgkmcnt(3)
	v_mfma_f32_16x16x32_bf16 v[222:225], v[222:225], v[4:7], v[252:255]
	s_waitcnt lgkmcnt(1)
	v_mfma_f32_16x16x32_bf16 v[230:233], v[230:233], v[4:7], v[252:255]
	v_mfma_f32_16x16x32_bf16 v[222:225], v[226:229], v[8:11], v[222:225]
	ds_read_b128 v[226:229], v171 offset:1152
	ds_read_b128 v[238:241], v171 offset:1216
	s_waitcnt lgkmcnt(2)
	v_mfma_f32_16x16x32_bf16 v[230:233], v[234:237], v[8:11], v[230:233]
	ds_read_b128 v[234:237], v171 offset:2240
	ds_read_b128 v[242:245], v171 offset:2304
	s_nop 2
	v_exp_f32_e32 v3, v223
	v_exp_f32_e32 v219, v225
	s_waitcnt lgkmcnt(3)
	v_mfma_f32_16x16x32_bf16 v[226:229], v[226:229], v[12:15], v[252:255]
	v_exp_f32_e32 v225, v231
	s_nop 1
	s_waitcnt lgkmcnt(2)
	v_mfma_f32_16x16x32_bf16 v[226:229], v[238:241], v[16:19], v[226:229]
	v_add3_u32 v0, s13, v134, v135
	v_exp_f32_e32 v217, v224
	s_waitcnt lgkmcnt(1)
	v_mfma_f32_16x16x32_bf16 v[172:175], v[234:237], v[12:15], v[252:255]
	ds_read_b128 v[234:237], v0 offset:18432
	ds_read_b128 v[238:241], v0 offset:20736
	s_nop 1
	v_exp_f32_e32 v2, v226
	v_exp_f32_e32 v171, v227
	s_waitcnt lgkmcnt(2)
	v_mfma_f32_16x16x32_bf16 v[172:175], v[242:245], v[16:19], v[172:175]
	ds_read_b128 v[242:245], v0 offset:23040
	ds_read_b128 v[246:249], v0 offset:25344
	v_exp_f32_e32 v0, v222
	v_exp_f32_e32 v218, v228
	v_exp_f32_e32 v223, v229
	v_exp_f32_e32 v222, v230
	s_nop 1
	v_exp_f32_e32 v224, v172
	v_exp_f32_e32 v226, v173
	v_exp_f32_e32 v227, v232
	v_exp_f32_e32 v228, v174
	v_exp_f32_e32 v229, v233
	v_exp_f32_e32 v230, v175
	v_cvt_pk_bf16_f32 v172, v0, v3
	v_cvt_pk_bf16_f32 v173, v217, v219
	v_cvt_pk_bf16_f32 v174, v222, v225
	v_cvt_pk_bf16_f32 v175, v227, v229
	v_cvt_pk_bf16_f32 v222, v2, v171
	v_cvt_pk_bf16_f32 v223, v218, v223
	v_cvt_pk_bf16_f32 v224, v224, v226
	v_cvt_pk_bf16_f32 v225, v228, v230
	v_add3_u32 v0, s13, v135, v134
	s_waitcnt lgkmcnt(3)
	v_mfma_f32_16x16x32_bf16 v[104:107], v[234:237], v[172:175], v[104:107]
	ds_read_b128 v[226:229], v0 offset:27648
	ds_read_b128 v[230:233], v0 offset:29952
	v_mfma_f32_16x16x32_bf16 v[112:115], v[234:237], v[222:225], v[112:115]
	ds_read_b128 v[234:237], v0 offset:32256
	s_waitcnt lgkmcnt(5)
	v_mfma_f32_16x16x32_bf16 v[100:103], v[238:241], v[172:175], v[100:103]
	v_mfma_f32_16x16x32_bf16 v[108:111], v[238:241], v[222:225], v[108:111]
	ds_read_b128 v[238:241], v0 offset:34560
	s_waitcnt lgkmcnt(5)
	v_mfma_f32_16x16x32_bf16 v[88:91], v[242:245], v[172:175], v[88:91]
	v_mfma_f32_16x16x32_bf16 v[96:99], v[242:245], v[222:225], v[96:99]
	s_waitcnt lgkmcnt(4)
	v_mfma_f32_16x16x32_bf16 v[84:87], v[246:249], v[172:175], v[84:87]
	v_mfma_f32_16x16x32_bf16 v[92:95], v[246:249], v[222:225], v[92:95]
	s_mov_b32 s66, s64
	s_mov_b32 s67, s64
	s_waitcnt lgkmcnt(3)
	v_mfma_f32_16x16x32_bf16 v[72:75], v[226:229], v[172:175], v[72:75]
	s_mov_b32 s65, s64
	v_mfma_f32_16x16x32_bf16 v[80:83], v[226:229], v[222:225], v[80:83]
	v_mov_b64_e32 v[228:229], s[66:67]
	v_mov_b64_e32 v[226:227], s[64:65]
	s_waitcnt lgkmcnt(2)
	v_mfma_f32_16x16x32_bf16 v[68:71], v[230:233], v[172:175], v[68:71]
	v_mfma_f32_16x16x32_bf16 v[76:79], v[230:233], v[222:225], v[76:79]
	s_waitcnt lgkmcnt(1)
	v_mfma_f32_16x16x32_bf16 v[56:59], v[234:237], v[172:175], v[56:59]
	v_mfma_f32_16x16x32_bf16 v[64:67], v[234:237], v[222:225], v[64:67]
	s_waitcnt lgkmcnt(0)
	v_mfma_f32_16x16x32_bf16 v[52:55], v[238:241], v[172:175], v[52:55]
	v_mfma_f32_16x16x32_bf16 v[60:63], v[238:241], v[222:225], v[60:63]
	v_mfma_f32_16x16x32_bf16 v[128:131], v[226:229], v[172:175], v[128:131]
	v_mfma_f32_16x16x32_bf16 v[116:119], v[226:229], v[222:225], v[116:119]
	s_branch .LBB0_142

.LBB0_143:
	s_lshl_b32 s10, s29, 5
	s_or_b32 s16, s10, s62
	v_cmp_le_i32_e32 vcc, s16, v161
	s_and_saveexec_b64 s[10:11], vcc
	s_cbranch_execz .LBB0_142
	s_or_b32 s17, s16, 31
	v_mov_b32_e32 v171, v170
	v_cmp_ge_i32_e64 s[44:45], s17, v159
	s_nop 1
	s_cmp_eq_u64 s[44:45], 0
	s_cbranch_scc1 .Lfar_a2
	v_mov_b64_e32 v[172:173], v[170:171]
	v_mov_b64_e32 v[2:3], v[170:171]
	v_mov_b64_e32 v[174:175], v[170:171]
	s_and_saveexec_b64 s[12:13], s[44:45]
	s_xor_b64 s[12:13], exec, s[12:13]
	s_cbranch_execz .LBB0_162
	v_or_b32_e32 v171, s16, v132
	v_sub_u32_e32 v0, v207, v171
	v_cmp_le_i32_e64 s[46:47], s17, v163
	v_cmp_lt_i32_e64 s[48:49], -1, v0
	v_cmp_gt_i32_e64 s[44:45], s17, v163
	s_or_b64 s[18:19], s[46:47], s[48:49]
	v_mov_b32_e32 v3, 0xf149f2ca
	v_mov_b32_e32 v2, 0xf149f2ca
	s_and_saveexec_b64 s[16:17], s[18:19]
	v_med3_i32 v0, v0, 0, v186
	v_lshl_add_u32 v0, v0, 2, 0
	ds_read_b32 v2, v0
	s_or_b64 exec, exec, s[16:17]
	v_xad_u32 v0, v171, -1, v207
	v_cmp_lt_i32_e64 s[46:47], -1, v0
	s_xor_b64 s[16:17], s[44:45], -1
	s_or_b64 s[44:45], s[16:17], s[46:47]
	s_and_saveexec_b64 s[18:19], s[44:45]
	v_med3_i32 v0, v0, 0, v186
	v_lshl_add_u32 v0, v0, 2, 0
	ds_read_b32 v3, v0
	s_or_b64 exec, exec, s[18:19]
	v_or_b32_e32 v0, 2, v171
	v_sub_u32_e32 v0, v207, v0
	v_cmp_lt_i32_e64 s[44:45], -1, v0
	s_or_b64 s[44:45], s[16:17], s[44:45]
	v_mov_b32_e32 v173, 0xf149f2ca
	v_mov_b32_e32 v172, 0xf149f2ca
	s_and_saveexec_b64 s[18:19], s[44:45]
	v_med3_i32 v0, v0, 0, v186
	v_lshl_add_u32 v0, v0, 2, 0
	ds_read_b32 v172, v0
	s_or_b64 exec, exec, s[18:19]
	v_or_b32_e32 v0, 3, v171
	v_sub_u32_e32 v0, v207, v0
	v_cmp_lt_i32_e64 s[44:45], -1, v0
	s_or_b64 s[44:45], s[16:17], s[44:45]
	s_and_saveexec_b64 s[18:19], s[44:45]
	v_med3_i32 v0, v0, 0, v186
	v_lshl_add_u32 v0, v0, 2, 0
	ds_read_b32 v173, v0
	s_or_b64 exec, exec, s[18:19]
	v_or_b32_e32 v0, 4, v171
	v_sub_u32_e32 v0, v207, v0
	v_cmp_lt_i32_e64 s[44:45], -1, v0
	s_or_b64 s[44:45], s[16:17], s[44:45]
	v_mov_b32_e32 v175, 0xf149f2ca
	v_mov_b32_e32 v174, 0xf149f2ca
	s_and_saveexec_b64 s[18:19], s[44:45]
	v_med3_i32 v0, v0, 0, v186
	v_lshl_add_u32 v0, v0, 2, 0
	ds_read_b32 v174, v0
	s_or_b64 exec, exec, s[18:19]
	v_or_b32_e32 v0, 5, v171
	v_sub_u32_e32 v0, v207, v0
	v_cmp_lt_i32_e64 s[44:45], -1, v0
	s_or_b64 s[44:45], s[16:17], s[44:45]
	s_and_saveexec_b64 s[18:19], s[44:45]
	v_med3_i32 v0, v0, 0, v186
	v_lshl_add_u32 v0, v0, 2, 0
	ds_read_b32 v175, v0
	s_or_b64 exec, exec, s[18:19]
	v_or_b32_e32 v0, 6, v171
	v_sub_u32_e32 v218, v207, v0
	v_cmp_lt_i32_e64 s[44:45], -1, v218
	s_or_b64 s[44:45], s[16:17], s[44:45]
	v_mov_b32_e32 v217, 0xf149f2ca
	v_mov_b32_e32 v0, 0xf149f2ca
	s_and_saveexec_b64 s[18:19], s[44:45]
	v_med3_i32 v0, v218, 0, v186
	v_lshl_add_u32 v0, v0, 2, 0
	ds_read_b32 v0, v0
	s_or_b64 exec, exec, s[18:19]
	v_or_b32_e32 v171, 7, v171
	v_sub_u32_e32 v171, v207, v171
	v_cmp_lt_i32_e64 s[44:45], -1, v171
	s_or_b64 s[18:19], s[16:17], s[44:45]
	s_and_saveexec_b64 s[16:17], s[18:19]
	v_med3_i32 v171, v171, 0, v186
	v_lshl_add_u32 v171, v171, 2, 0
	ds_read_b32 v217, v171
	s_or_b64 exec, exec, s[16:17]

.Lfar_b2:
	s_lshl_b32 s13, s29, 6
	s_mul_i32 s12, s29, 0x2200
	s_add_i32 s13, s13, 0
	v_add_u32_e32 v171, s12, v139
	ds_read_b128 v[222:225], v171 offset:36864
	ds_read_b128 v[226:229], v171 offset:36928
	ds_read_b128 v[230:233], v171 offset:37952
	ds_read_b128 v[234:237], v171 offset:38016
	s_waitcnt lgkmcnt(4)
	s_waitcnt lgkmcnt(3)
	v_mfma_f32_16x16x32_bf16 v[222:225], v[222:225], v[4:7], v[252:255]
	s_waitcnt lgkmcnt(1)
	v_mfma_f32_16x16x32_bf16 v[230:233], v[230:233], v[4:7], v[252:255]
	v_mfma_f32_16x16x32_bf16 v[222:225], v[226:229], v[8:11], v[222:225]
	ds_read_b128 v[226:229], v171 offset:36992
	ds_read_b128 v[238:241], v171 offset:37056
	s_waitcnt lgkmcnt(2)
	v_mfma_f32_16x16x32_bf16 v[230:233], v[234:237], v[8:11], v[230:233]
	ds_read_b128 v[234:237], v171 offset:38080
	ds_read_b128 v[242:245], v171 offset:38144
	s_nop 2
	v_exp_f32_e32 v3, v223
	v_exp_f32_e32 v219, v225
	s_waitcnt lgkmcnt(3)
	v_mfma_f32_16x16x32_bf16 v[226:229], v[226:229], v[12:15], v[252:255]
	v_exp_f32_e32 v225, v231
	s_nop 1
	s_waitcnt lgkmcnt(2)
	v_mfma_f32_16x16x32_bf16 v[226:229], v[238:241], v[16:19], v[226:229]
	v_add3_u32 v0, s13, v134, v135
	v_exp_f32_e32 v217, v224
	s_waitcnt lgkmcnt(1)
	v_mfma_f32_16x16x32_bf16 v[172:175], v[234:237], v[12:15], v[252:255]
	ds_read_b128 v[234:237], v0 offset:54272
	ds_read_b128 v[238:241], v0 offset:56576
	s_nop 1
	v_exp_f32_e32 v2, v226
	v_exp_f32_e32 v171, v227
	s_waitcnt lgkmcnt(2)
	v_mfma_f32_16x16x32_bf16 v[172:175], v[242:245], v[16:19], v[172:175]
	ds_read_b128 v[242:245], v0 offset:58880
	ds_read_b128 v[246:249], v0 offset:61184
	v_exp_f32_e32 v0, v222
	v_exp_f32_e32 v218, v228
	v_exp_f32_e32 v223, v229
	v_exp_f32_e32 v222, v230
	s_nop 1
	v_exp_f32_e32 v224, v172
	v_exp_f32_e32 v226, v173
	v_exp_f32_e32 v227, v232
	v_exp_f32_e32 v228, v174
	v_exp_f32_e32 v229, v233
	v_exp_f32_e32 v230, v175
	v_cvt_pk_bf16_f32 v172, v0, v3
	v_cvt_pk_bf16_f32 v173, v217, v219
	v_cvt_pk_bf16_f32 v174, v222, v225
	v_cvt_pk_bf16_f32 v175, v227, v229
	v_cvt_pk_bf16_f32 v222, v2, v171
	v_cvt_pk_bf16_f32 v223, v218, v223
	v_cvt_pk_bf16_f32 v224, v224, v226
	v_cvt_pk_bf16_f32 v225, v228, v230
	v_add3_u32 v0, s13, v135, v134
	v_add_u32_e32 v2, 0x10100, v0
	ds_read_b128 v[226:229], v0 offset:63488
	ds_read_b128 v[230:233], v2
	v_add_u32_e32 v2, 0x10a00, v0
	v_add_u32_e32 v0, 0x11300, v0
	s_waitcnt lgkmcnt(5)
	v_mfma_f32_16x16x32_bf16 v[104:107], v[234:237], v[172:175], v[104:107]
	v_mfma_f32_16x16x32_bf16 v[112:115], v[234:237], v[222:225], v[112:115]
	ds_read_b128 v[234:237], v2
	s_waitcnt lgkmcnt(5)
	v_mfma_f32_16x16x32_bf16 v[100:103], v[238:241], v[172:175], v[100:103]
	v_mfma_f32_16x16x32_bf16 v[108:111], v[238:241], v[222:225], v[108:111]
	ds_read_b128 v[238:241], v0
	s_waitcnt lgkmcnt(5)
	v_mfma_f32_16x16x32_bf16 v[88:91], v[242:245], v[172:175], v[88:91]
	v_mfma_f32_16x16x32_bf16 v[96:99], v[242:245], v[222:225], v[96:99]
	s_waitcnt lgkmcnt(4)
	v_mfma_f32_16x16x32_bf16 v[84:87], v[246:249], v[172:175], v[84:87]
	v_mfma_f32_16x16x32_bf16 v[92:95], v[246:249], v[222:225], v[92:95]
	s_mov_b32 s66, s64
	s_mov_b32 s67, s64
	s_waitcnt lgkmcnt(3)
	v_mfma_f32_16x16x32_bf16 v[72:75], v[226:229], v[172:175], v[72:75]
	s_mov_b32 s65, s64
	v_mfma_f32_16x16x32_bf16 v[80:83], v[226:229], v[222:225], v[80:83]
	v_mov_b64_e32 v[228:229], s[66:67]
	v_mov_b64_e32 v[226:227], s[64:65]
	s_waitcnt lgkmcnt(2)
	v_mfma_f32_16x16x32_bf16 v[68:71], v[230:233], v[172:175], v[68:71]
	v_mfma_f32_16x16x32_bf16 v[76:79], v[230:233], v[222:225], v[76:79]
	s_waitcnt lgkmcnt(1)
	v_mfma_f32_16x16x32_bf16 v[56:59], v[234:237], v[172:175], v[56:59]
	v_mfma_f32_16x16x32_bf16 v[64:67], v[234:237], v[222:225], v[64:67]
	s_waitcnt lgkmcnt(0)
	v_mfma_f32_16x16x32_bf16 v[52:55], v[238:241], v[172:175], v[52:55]
	v_mfma_f32_16x16x32_bf16 v[60:63], v[238:241], v[222:225], v[60:63]
	v_mfma_f32_16x16x32_bf16 v[128:131], v[226:229], v[172:175], v[128:131]
	v_mfma_f32_16x16x32_bf16 v[116:119], v[226:229], v[222:225], v[116:119]
	s_branch .LBB0_168

.LBB0_169:
	s_lshl_b32 s10, s29, 5
	s_or_b32 s63, s10, s62
	v_cmp_le_i32_e32 vcc, s63, v208
	s_and_saveexec_b64 s[10:11], vcc
	s_cbranch_execz .LBB0_168
	s_or_b32 s16, s63, 0x5f
	v_mov_b32_e32 v171, v170
	v_cmp_ge_i32_e64 s[44:45], s16, v159
	s_nop 1
	s_cmp_eq_u64 s[44:45], 0
	s_cbranch_scc1 .Lfar_b2
	v_mov_b64_e32 v[172:173], v[170:171]
	v_mov_b64_e32 v[2:3], v[170:171]
	v_mov_b64_e32 v[174:175], v[170:171]
	s_and_saveexec_b64 s[12:13], s[44:45]
	s_xor_b64 s[12:13], exec, s[12:13]
	s_cbranch_execz .LBB0_188
	v_subrev_u32_e32 v0, s63, v197
	v_add_u32_e32 v0, v0, v209
	v_cmp_le_i32_e64 s[46:47], s16, v163
	v_cmp_lt_i32_e64 s[48:49], -1, v0
	v_cmp_gt_i32_e64 s[44:45], s16, v163
	s_or_b64 s[18:19], s[46:47], s[48:49]
	v_mov_b32_e32 v3, 0xf149f2ca
	v_mov_b32_e32 v2, 0xf149f2ca
	s_and_saveexec_b64 s[16:17], s[18:19]
	v_med3_i32 v0, v0, 0, v186
	v_lshl_add_u32 v0, v0, 2, 0
	ds_read_b32 v2, v0
	s_or_b64 exec, exec, s[16:17]
	v_xad_u32 v0, s63, -1, v210
	v_cmp_lt_i32_e64 s[46:47], -1, v0
	s_xor_b64 s[16:17], s[44:45], -1
	s_or_b64 s[44:45], s[16:17], s[46:47]
	s_and_saveexec_b64 s[18:19], s[44:45]
	v_med3_i32 v0, v0, 0, v186
	v_lshl_add_u32 v0, v0, 2, 0
	ds_read_b32 v3, v0
	s_or_b64 exec, exec, s[18:19]
	v_subrev_u32_e32 v0, s63, v211
	v_cmp_lt_i32_e64 s[44:45], -1, v0
	s_or_b64 s[44:45], s[16:17], s[44:45]
	v_mov_b32_e32 v173, 0xf149f2ca
	v_mov_b32_e32 v172, 0xf149f2ca
	s_and_saveexec_b64 s[18:19], s[44:45]
	v_med3_i32 v0, v0, 0, v186
	v_lshl_add_u32 v0, v0, 2, 0
	ds_read_b32 v172, v0
	s_or_b64 exec, exec, s[18:19]
	v_subrev_u32_e32 v0, s63, v212
	v_cmp_lt_i32_e64 s[44:45], -1, v0
	s_or_b64 s[44:45], s[16:17], s[44:45]
	s_and_saveexec_b64 s[18:19], s[44:45]
	v_med3_i32 v0, v0, 0, v186
	v_lshl_add_u32 v0, v0, 2, 0
	ds_read_b32 v173, v0
	s_or_b64 exec, exec, s[18:19]
	v_subrev_u32_e32 v0, s63, v213
	v_cmp_lt_i32_e64 s[44:45], -1, v0
	s_or_b64 s[44:45], s[16:17], s[44:45]
	v_mov_b32_e32 v175, 0xf149f2ca
	v_mov_b32_e32 v174, 0xf149f2ca
	s_and_saveexec_b64 s[18:19], s[44:45]
	v_med3_i32 v0, v0, 0, v186
	v_lshl_add_u32 v0, v0, 2, 0
	ds_read_b32 v174, v0
	s_or_b64 exec, exec, s[18:19]
	v_subrev_u32_e32 v0, s63, v214
	v_cmp_lt_i32_e64 s[44:45], -1, v0
	s_or_b64 s[44:45], s[16:17], s[44:45]
	s_and_saveexec_b64 s[18:19], s[44:45]
	v_med3_i32 v0, v0, 0, v186
	v_lshl_add_u32 v0, v0, 2, 0
	ds_read_b32 v175, v0
	s_or_b64 exec, exec, s[18:19]
	v_subrev_u32_e32 v171, s63, v215
	v_cmp_lt_i32_e64 s[44:45], -1, v171
	s_or_b64 s[44:45], s[16:17], s[44:45]
	v_mov_b32_e32 v217, 0xf149f2ca
	v_mov_b32_e32 v0, 0xf149f2ca
	s_and_saveexec_b64 s[18:19], s[44:45]
	v_med3_i32 v0, v171, 0, v186
	v_lshl_add_u32 v0, v0, 2, 0
	ds_read_b32 v0, v0
	s_or_b64 exec, exec, s[18:19]
	v_subrev_u32_e32 v171, s63, v216
	v_cmp_lt_i32_e64 s[44:45], -1, v171
	s_or_b64 s[18:19], s[16:17], s[44:45]
	s_and_saveexec_b64 s[16:17], s[18:19]
	v_med3_i32 v171, v171, 0, v186
	v_lshl_add_u32 v171, v171, 2, 0
	ds_read_b32 v217, v171
	s_or_b64 exec, exec, s[16:17]
